# GEMM1 epilogue: direct 16-byte stores from registers via permlane16_swap (no LDS staging, no block barrier)
# baseline (speedup 1.0000x reference)
.LBB0_355:
	s_or_b64 exec, exec, s[2:3]
	v_lshrrev_b32_e32 v56, 2, v95
	v_and_b32_e32 v57, 1, v56
	v_lshrrev_b32_e32 v58, 1, v56
	v_lshlrev_b32_e32 v57, 4, v57
	v_lshl_add_u32 v57, v58, 3, v57
	v_add_u32_e32 v57, v94, v57
	v_add_u32_e32 v58, 32, v57
	v_cmp_gt_i32_e64 s[4:5], s19, v57
	v_cmp_gt_i32_e64 s[6:7], s19, v58
	v_lshl_or_b32 v59, v92, 6, v93
	v_add_u32_e32 v59, s8, v59
	v_lshlrev_b32_e32 v84, 1, v57
	v_mov_b32_e32 v85, 0
	v_mad_u64_u32 v[196:197], s[2:3], v59, s29, v[84:85]
	v_lshl_add_u64 v[196:197], s[50:51], 0, v[196:197]
	s_mov_b32 s9, 0x18400
	v_add_co_u32_e32 v198, vcc, s9, v196
	s_nop 1
	v_addc_co_u32_e32 v199, vcc, 0, v197, vcc
	v_add_co_u32_e32 v200, vcc, s9, v198
	s_nop 1
	v_addc_co_u32_e32 v201, vcc, 0, v199, vcc
	v_add_co_u32_e32 v202, vcc, s9, v200
	s_nop 1
	v_addc_co_u32_e32 v203, vcc, 0, v201, vcc
	v_cvt_pk_bf16_f32 v164, v60, v61
	v_cvt_pk_bf16_f32 v165, v62, v63
	v_cvt_pk_bf16_f32 v166, v72, v73
	v_cvt_pk_bf16_f32 v167, v74, v75
	v_cvt_pk_bf16_f32 v168, v32, v33
	v_cvt_pk_bf16_f32 v169, v34, v35
	v_cvt_pk_bf16_f32 v170, v16, v17
	v_cvt_pk_bf16_f32 v171, v18, v19
	v_cvt_pk_bf16_f32 v172, v68, v69
	v_cvt_pk_bf16_f32 v173, v70, v71
	v_cvt_pk_bf16_f32 v174, v48, v49
	v_cvt_pk_bf16_f32 v175, v50, v51
	v_cvt_pk_bf16_f32 v176, v28, v29
	v_cvt_pk_bf16_f32 v177, v30, v31
	v_cvt_pk_bf16_f32 v178, v12, v13
	v_cvt_pk_bf16_f32 v179, v14, v15
	v_cvt_pk_bf16_f32 v180, v52, v53
	v_cvt_pk_bf16_f32 v181, v54, v55
	v_cvt_pk_bf16_f32 v182, v44, v45
	v_cvt_pk_bf16_f32 v183, v46, v47
	v_cvt_pk_bf16_f32 v184, v24, v25
	v_cvt_pk_bf16_f32 v185, v26, v27
	v_cvt_pk_bf16_f32 v186, v8, v9
	v_cvt_pk_bf16_f32 v187, v10, v11
	v_cvt_pk_bf16_f32 v188, v40, v41
	v_cvt_pk_bf16_f32 v189, v42, v43
	v_cvt_pk_bf16_f32 v190, v36, v37
	v_cvt_pk_bf16_f32 v191, v38, v39
	v_cvt_pk_bf16_f32 v192, v20, v21
	v_cvt_pk_bf16_f32 v193, v22, v23
	v_cvt_pk_bf16_f32 v194, v4, v5
	v_cvt_pk_bf16_f32 v195, v6, v7
	s_nop 1
	v_permlane16_swap_b32_e32 v164, v166
	v_permlane16_swap_b32_e32 v165, v167
	v_permlane16_swap_b32_e32 v168, v170
	v_permlane16_swap_b32_e32 v169, v171
	v_permlane16_swap_b32_e32 v172, v174
	v_permlane16_swap_b32_e32 v173, v175
	v_permlane16_swap_b32_e32 v176, v178
	v_permlane16_swap_b32_e32 v177, v179
	v_permlane16_swap_b32_e32 v180, v182
	v_permlane16_swap_b32_e32 v181, v183
	v_permlane16_swap_b32_e32 v184, v186
	v_permlane16_swap_b32_e32 v185, v187
	v_permlane16_swap_b32_e32 v188, v190
	v_permlane16_swap_b32_e32 v189, v191
	v_permlane16_swap_b32_e32 v192, v194
	v_permlane16_swap_b32_e32 v193, v195
	s_mov_b64 s[2:3], exec
	s_and_b64 vcc, exec, s[58:59]
	s_cbranch_vccz .Lepi_plain
	s_and_b64 exec, s[2:3], s[4:5]
	s_cbranch_execz .Lepi_g_p1
	global_store_dwordx4 v[196:197], v[164:167], off sc1
	global_store_dwordx4 v[198:199], v[172:175], off sc1
	global_store_dwordx4 v[200:201], v[180:183], off sc1
	global_store_dwordx4 v[202:203], v[188:191], off sc1
.Lepi_g_p1:
	s_and_b64 exec, s[2:3], s[6:7]
	s_cbranch_execz .Lepi_g_end
	global_store_dwordx4 v[196:197], v[168:171], off offset:64 sc1
	global_store_dwordx4 v[198:199], v[176:179], off offset:64 sc1
	global_store_dwordx4 v[200:201], v[184:187], off offset:64 sc1
	global_store_dwordx4 v[202:203], v[192:195], off offset:64 sc1

.Lepi_plain:
	s_and_b64 exec, s[2:3], s[4:5]
	s_cbranch_execz .Lepi_n_p1
	global_store_dwordx4 v[196:197], v[164:167], off
	global_store_dwordx4 v[198:199], v[172:175], off
	global_store_dwordx4 v[200:201], v[180:183], off
	global_store_dwordx4 v[202:203], v[188:191], off
.Lepi_n_p1:
	s_and_b64 exec, s[2:3], s[6:7]
	s_cbranch_execz .Lepi_n_end
	global_store_dwordx4 v[196:197], v[168:171], off offset:64
	global_store_dwordx4 v[198:199], v[176:179], off offset:64
	global_store_dwordx4 v[200:201], v[184:187], off offset:64
	global_store_dwordx4 v[202:203], v[192:195], off offset:64
.Lepi_n_end:
.Lepi_done:
	s_mov_b64 exec, s[2:3]
	s_nop 1
